# speedup vs baseline: 1.0237x; 1.0052x over previous
; __device__ __forceinline__ float silu_f(float x) { return x * __builtin_amdgcn_rcpf(1.f + __expf(-x)); }
;     __device__ __forceinline__ void operator()(const f32x4 (&acc)[2][2][4][2], const Unit& u, int wr, int wc, int fr, int fq) const {
;         const int r0 = u.pm * BM + wr * 64 + fr, ch = 64 * u.pn + 16 * wc + 4 * fq, lane = fq * 16 + fr;
;         float rstd[2][4];
; #pragma unroll
;         for (int ai = 0; ai < 2; ++ai)
; #pragma unroll
;             for (int m = 0; m < 4; ++m) rstd[ai][m] = (float)ss[r0 + ai * HALF + m * 16] * (1.f / 16777216.f);
;         const f32x4 w0 = *(const f32x4*)(cw + ch), w1 = *(const f32x4*)(cw + 2048 + ch), w2 = *(const f32x4*)(cw + 4096 + ch);
;         const bool fuse = u.pm != 96;
;         const int lr = (lane & 48) | ((fr + 15) & 15), ll = (lane & 48) | ((fr + 1) & 15);
; #pragma unroll
;         for (int ai = 0; ai < 2; ++ai) {
;             f32x4 g[4], cu[4];
; #pragma unroll
;             for (int m = 0; m < 4; ++m) {
;                 const float rs = __builtin_amdgcn_rsqf(rstd[ai][m] * (1.f / 2048.f) + 1e-6f);
;                 const f32x4 b = acc[ai][0][m][0] * rs, z = acc[ai][0][m][1] * rs, c = acc[ai][1][m][0] * rs, uu = acc[ai][1][m][1] * rs;
; #pragma unroll
;                 for (int j = 0; j < 4; ++j) { g[m][j] = b[j] * silu_f(z[j]); cu[m][j] = c[j] * uu[j]; }
;             }
.LBB0_301:
	v_lshl_add_u32 v148, s72, 8, v164
	v_ashrrev_i32_e32 v149, 31, v148
	v_lshl_add_u64 v[64:65], v[148:149], 3, s[92:93]
	global_load_dwordx2 v[66:67], v[64:65], off
	v_lshl_or_b32 v146, s64, 6, v166
	v_ashrrev_i32_e32 v147, 31, v146
	v_lshlrev_b64 v[72:73], 2, v[146:147]
	s_cmpk_lg_i32 s72, 0x60
	v_or_b32_e32 v150, 16, v148
	v_or_b32_e32 v154, 32, v148
	v_or_b32_e32 v160, 48, v148
	s_cselect_b64 s[72:73], -1, 0
	v_ashrrev_i32_e32 v151, 31, v150
	v_ashrrev_i32_e32 v155, 31, v154
	v_ashrrev_i32_e32 v161, 31, v160
	s_and_b64 vcc, exec, s[72:73]
	s_movk_i32 s94, 0x5fff
	s_waitcnt vmcnt(0)
	v_ffbh_u32_e32 v68, v67
	v_min_u32_e32 v68, 32, v68
	v_lshlrev_b64 v[66:67], v68, v[66:67]
	v_min_u32_e32 v66, 1, v66
	v_or_b32_e32 v66, v67, v66
	v_cvt_f32_u32_e32 v66, v66
	v_sub_u32_e32 v67, 32, v68
	v_ldexp_f32 v66, v66, v67
	v_mul_f32_e32 v173, 0x33800000, v66
	global_load_dwordx2 v[66:67], v[64:65], off offset:128
	v_fmamk_f32 v173, v173, 0x3a000000, v227
	v_rsq_f32_e32 v173, v173
	s_waitcnt vmcnt(0)
	v_ffbh_u32_e32 v68, v67
	v_min_u32_e32 v68, 32, v68
	v_lshlrev_b64 v[66:67], v68, v[66:67]
	v_min_u32_e32 v66, 1, v66
	v_or_b32_e32 v66, v67, v66
	v_cvt_f32_u32_e32 v66, v66
	v_sub_u32_e32 v67, 32, v68
	v_mul_f32_e32 v132, v132, v173
	v_mul_f32_e32 v174, 0xbfb8aa3b, v132
	v_ldexp_f32 v66, v66, v67
	v_mul_f32_e32 v172, 0x33800000, v66
	global_load_dwordx2 v[66:67], v[64:65], off offset:256
	v_exp_f32_e32 v174, v174
	v_mul_f32_e32 v136, v136, v173
	v_mul_f32_e32 v133, v133, v173
	v_mul_f32_e32 v128, v128, v173
	v_add_f32_e32 v174, 1.0, v174
	v_rcp_f32_e32 v174, v174
	v_mul_f32_e32 v124, v124, v173
	v_mul_f32_e32 v124, v128, v124
	v_mul_f32_e32 v128, v137, v173
	v_mul_f32_e32 v132, v132, v174
	v_mul_f32_e32 v132, v136, v132
	v_mul_f32_e32 v136, 0xbfb8aa3b, v133
	v_exp_f32_e32 v136, v136
	v_mul_f32_e32 v129, v129, v173
	v_mul_f32_e32 v125, v125, v173
	v_mul_f32_e32 v125, v129, v125
	v_add_f32_e32 v136, 1.0, v136
	v_rcp_f32_e32 v136, v136
	v_mul_f32_e32 v129, v138, v173
	v_mul_f32_e32 v131, v131, v173
	v_mul_f32_e32 v127, v127, v173
	v_mul_f32_e32 v133, v133, v136
	v_mul_f32_e32 v128, v128, v133
	v_mul_f32_e32 v133, v134, v173
	v_mul_f32_e32 v134, 0xbfb8aa3b, v133
	v_exp_f32_e32 v134, v134
	v_mul_f32_e32 v127, v131, v127
	v_fmamk_f32 v131, v172, 0x3a000000, v227
	v_rsq_f32_e32 v131, v131
	v_add_f32_e32 v134, 1.0, v134
	v_rcp_f32_e32 v134, v134
	v_mul_f32_e32 v130, v130, v173
	v_mul_f32_e32 v126, v126, v173
	v_mul_f32_e32 v126, v130, v126
	v_mul_f32_e32 v133, v133, v134
	v_mul_f32_e32 v129, v129, v133
	v_mul_f32_e32 v133, v135, v173
	v_mul_f32_e32 v134, 0xbfb8aa3b, v133
	v_exp_f32_e32 v134, v134
	v_mul_f32_e32 v130, v139, v173
	v_mul_f32_e32 v116, v116, v131
	v_mul_f32_e32 v120, v120, v131
	v_add_f32_e32 v134, 1.0, v134
	v_rcp_f32_e32 v134, v134
	v_mul_f32_e32 v117, v117, v131
	v_mul_f32_e32 v112, v112, v131
	v_mul_f32_e32 v108, v108, v131
	v_mul_f32_e32 v133, v133, v134
	v_mul_f32_e32 v130, v130, v133
	v_mul_f32_e32 v133, 0xbfb8aa3b, v116
	v_exp_f32_e32 v133, v133
	v_mul_f32_e32 v108, v112, v108
	v_mul_f32_e32 v112, v121, v131
	v_mul_f32_e32 v113, v113, v131
	v_add_f32_e32 v133, 1.0, v133
	v_rcp_f32_e32 v133, v133
	v_mul_f32_e32 v109, v109, v131
	v_mul_f32_e32 v109, v113, v109
	v_mul_f32_e32 v113, v122, v131
	v_mul_f32_e32 v116, v116, v133
	v_mul_f32_e32 v116, v120, v116
	v_mul_f32_e32 v120, 0xbfb8aa3b, v117
	v_exp_f32_e32 v120, v120
	v_mul_f32_e32 v115, v115, v131
	v_mul_f32_e32 v111, v111, v131
	v_mul_f32_e32 v111, v115, v111
	v_add_f32_e32 v120, 1.0, v120
	v_rcp_f32_e32 v120, v120
	v_mul_f32_e32 v114, v114, v131
	v_mul_f32_e32 v110, v110, v131
	v_mul_f32_e32 v110, v114, v110
	v_mul_f32_e32 v117, v117, v120
	v_mul_f32_e32 v112, v112, v117
	v_mul_f32_e32 v117, v118, v131
	v_mul_f32_e32 v118, 0xbfb8aa3b, v117
	v_exp_f32_e32 v118, v118
	v_mul_f32_e32 v114, v123, v131
	s_waitcnt vmcnt(0)
	v_ffbh_u32_e32 v68, v67
	v_min_u32_e32 v68, 32, v68
	v_lshlrev_b64 v[66:67], v68, v[66:67]
	v_min_u32_e32 v66, 1, v66
	v_or_b32_e32 v66, v67, v66
	v_cvt_f32_u32_e32 v66, v66
	v_sub_u32_e32 v67, 32, v68
	v_add_f32_e32 v118, 1.0, v118
	v_rcp_f32_e32 v118, v118
	v_ldexp_f32 v66, v66, v67
	v_mul_f32_e32 v171, 0x33800000, v66
	global_load_dwordx2 v[66:67], v[64:65], off offset:384
	v_mul_f32_e32 v117, v117, v118
	v_mul_f32_e32 v113, v113, v117
	v_mul_f32_e32 v117, v119, v131
	v_mul_f32_e32 v118, 0xbfb8aa3b, v117
	v_exp_f32_e32 v118, v118
	v_fmamk_f32 v115, v171, 0x3a000000, v227
	v_rsq_f32_e32 v115, v115
	global_load_dwordx2 v[162:163], v[64:65], off offset:1024
	global_load_dwordx2 v[158:159], v[64:65], off offset:1152
	global_load_dwordx2 v[156:157], v[64:65], off offset:1280
	global_load_dwordx2 v[152:153], v[64:65], off offset:1408
	v_add_f32_e32 v118, 1.0, v118
	v_rcp_f32_e32 v118, v118
	v_mul_f32_e32 v100, v100, v115
	v_mul_f32_e32 v104, v104, v115
	v_mul_f32_e32 v96, v96, v115
	v_mul_f32_e32 v117, v117, v118
	v_mul_f32_e32 v114, v114, v117
	v_mul_f32_e32 v117, 0xbfb8aa3b, v100
	v_exp_f32_e32 v117, v117
	v_mul_f32_e32 v92, v92, v115
	v_mul_f32_e32 v93, v93, v115
	v_lshl_add_u64 v[64:65], s[56:57], 0, v[72:73]
	v_add_f32_e32 v117, 1.0, v117
	v_rcp_f32_e32 v117, v117
	s_waitcnt vmcnt(4)
; __device__ __forceinline__ unsigned cvt_pk_bf16(float lo, float hi) { unsigned r; asm volatile("v_cvt_pk_bf16_f32 %0, %1, %2" : "=v"(r) : "v"(lo), "v"(hi)); return r; }
; __device__ __forceinline__ float silu_f(float x) { return x * __builtin_amdgcn_rcpf(1.f + __expf(-x)); }
;     __device__ __forceinline__ void operator()(const f32x4 (&acc)[2][2][4][2], const Unit& u, int wr, int wc, int fr, int fq) const {
;     ...
;                 const float rs = __builtin_amdgcn_rsqf(rstd[ai][m] * (1.f / 2048.f) + 1e-6f);
;                 const f32x4 b = acc[ai][0][m][0] * rs, z = acc[ai][0][m][1] * rs, c = acc[ai][1][m][0] * rs, uu = acc[ai][1][m][1] * rs;
; #pragma unroll
;                 for (int j = 0; j < 4; ++j) { g[m][j] = b[j] * silu_f(z[j]); cu[m][j] = c[j] * uu[j]; }
;             }
;             if (fuse) {
;                 f32x4 R[4], L[4];
; #pragma unroll
;                 for (int m = 0; m < 4; ++m)
; #pragma unroll
;                     for (int j = 0; j < 4; ++j) { R[m][j] = __shfl(cu[m][j], lr); L[m][j] = __shfl(cu[m][j], ll); }
; #pragma unroll
;                 for (int m = 0; m < 4; ++m) {
;                     const int r = r0 + ai * HALF + m * 16;
;                     const f32x4 prev = (fr == 0) ? R[m > 0 ? m - 1 : 0] : R[m], next = (fr == 15) ? L[m < 3 ? m + 1 : 3] : L[m];
;                     const bool edge = (m == 0 && fr == 0) || (m == 3 && fr == 15);
;                     f32x4 y;
; #pragma unroll
;                     for (int j = 0; j < 4; ++j) { const float t = g[m][j] * (prev[j] * w0[j] + cu[m][j] * w1[j] + next[j] * w2[j]); y[j] = edge ? g[m][j] : t; }
;                     const size_t off = (size_t)r * 2048 + ch;
;                     u32x2 o1; o1.x = cvt_pk_bf16(y[0], y[1]); o1.y = cvt_pk_bf16(y[2], y[3]);
;                     *(u32x2*)(G + off) = o1;
;                     if ((m == 0 && fr <= 1) || (m == 3 && fr >= 14)) { u32x2 o2; o2.x = cvt_pk_bf16(cu[m][0], cu[m][1]); o2.y = cvt_pk_bf16(cu[m][2], cu[m][3]); *(u32x2*)(CU + off) = o2; }
	v_ffbh_u32_e32 v68, v67
	v_mul_f32_e32 v100, v100, v117
	v_mul_f32_e32 v104, v104, v100
	v_mul_f32_e32 v100, v96, v92
	v_mul_f32_e32 v96, v101, v115
	v_mul_f32_e32 v101, 0xbfb8aa3b, v96
	v_exp_f32_e32 v101, v101
	v_min_u32_e32 v68, 32, v68
	v_lshlrev_b64 v[66:67], v68, v[66:67]
	v_min_u32_e32 v66, 1, v66
	v_add_f32_e32 v101, 1.0, v101
	v_rcp_f32_e32 v101, v101
	v_or_b32_e32 v66, v67, v66
	v_cvt_f32_u32_e32 v66, v66
	v_mul_f32_e32 v92, v105, v115
	v_mul_f32_e32 v96, v96, v101
	v_sub_u32_e32 v67, 32, v68
	v_mul_f32_e32 v105, v92, v96
	v_mul_f32_e32 v92, v97, v115
	v_ldexp_f32 v66, v66, v67
	v_lshl_add_u64 v[68:69], s[60:61], 0, v[72:73]
	v_lshl_add_u64 v[72:73], s[62:63], 0, v[72:73]
	v_mul_f32_e32 v101, v92, v93
	v_mul_f32_e32 v93, v102, v115
	v_mul_f32_e32 v170, 0x33800000, v66
	global_load_dwordx4 v[64:67], v[64:65], off
	v_mul_f32_e32 v96, 0xbfb8aa3b, v93
	global_load_dwordx4 v[68:71], v[68:69], off
	v_exp_f32_e32 v96, v96
	global_load_dwordx4 v[72:75], v[72:73], off
	v_mul_f32_e32 v92, v106, v115
	v_add_f32_e32 v96, 1.0, v96
	v_rcp_f32_e32 v96, v96
	s_nop 0
	v_mul_f32_e32 v93, v93, v96
	v_mul_f32_e32 v102, v92, v93
	v_mul_f32_e32 v92, v98, v115
	v_mul_f32_e32 v93, v94, v115
	v_mul_f32_e32 v98, v92, v93
	v_mul_f32_e32 v93, v103, v115
	v_mul_f32_e32 v94, 0xbfb8aa3b, v93
	v_exp_f32_e32 v94, v94
	v_mul_f32_e32 v92, v107, v115
	v_add_f32_e32 v94, 1.0, v94
	v_rcp_f32_e32 v94, v94
	s_nop 0
	v_mul_f32_e32 v93, v93, v94
	v_mul_f32_e32 v103, v92, v93
	v_mul_f32_e32 v92, v99, v115
	v_mul_f32_e32 v93, v95, v115
	v_mul_f32_e32 v99, v92, v93
	v_fmamk_f32 v92, v170, 0x3a000000, v227
	v_rsq_f32_e32 v92, v92
	s_nop 0
	v_mul_f32_e32 v84, v84, v92
	v_mul_f32_e32 v93, 0xbfb8aa3b, v84
	v_exp_f32_e32 v93, v93
	v_mul_f32_e32 v80, v80, v92
	v_mul_f32_e32 v76, v76, v92
	v_mul_f32_e32 v88, v88, v92
	v_add_f32_e32 v93, 1.0, v93
	v_rcp_f32_e32 v93, v93
	v_mul_f32_e32 v77, v77, v92
	v_mul_f32_e32 v78, v78, v92
	v_mul_f32_e32 v84, v84, v93
	v_mul_f32_e32 v93, v80, v76
	v_mul_f32_e32 v80, v85, v92
	v_mul_f32_e32 v106, v88, v84
	v_mul_f32_e32 v84, 0xbfb8aa3b, v80
	v_exp_f32_e32 v84, v84
	v_mul_f32_e32 v76, v89, v92
	v_add_f32_e32 v84, 1.0, v84
	v_rcp_f32_e32 v84, v84
	s_nop 0
	v_mul_f32_e32 v80, v80, v84
	v_mul_f32_e32 v107, v76, v80
	v_mul_f32_e32 v80, v86, v92
	v_mul_f32_e32 v76, v81, v92
	v_mul_f32_e32 v81, 0xbfb8aa3b, v80
	v_exp_f32_e32 v81, v81
	v_mul_f32_e32 v77, v76, v77
	v_mul_f32_e32 v76, v90, v92
	v_add_f32_e32 v81, 1.0, v81
	v_rcp_f32_e32 v81, v81
	s_nop 0
	v_mul_f32_e32 v80, v80, v81
	v_mul_f32_e32 v115, v76, v80
	v_mul_f32_e32 v76, v82, v92
	v_mul_f32_e32 v81, v76, v78
	v_mul_f32_e32 v78, v87, v92
	v_mul_f32_e32 v80, 0xbfb8aa3b, v78
	v_exp_f32_e32 v80, v80
	v_mul_f32_e32 v76, v91, v92
	v_add_f32_e32 v80, 1.0, v80
	v_rcp_f32_e32 v80, v80
	s_nop 0
	v_mul_f32_e32 v78, v78, v80
	v_mul_f32_e32 v117, v76, v78
	v_mul_f32_e32 v76, v83, v92
	v_mul_f32_e32 v78, v79, v92
	v_lshlrev_b64 v[82:83], 11, v[148:149]
	v_mul_f32_e32 v79, v76, v78
	v_lshl_add_u64 v[82:83], v[82:83], 0, v[146:147]
	s_cbranch_vccz .LBB0_307
	v_and_b32_e32 v76, 64, v232
	v_or_b32_e32 v78, v76, v167
	v_or_b32_e32 v76, v76, v168
	v_lshlrev_b32_e32 v78, 2, v78
	v_lshlrev_b32_e32 v84, 2, v76
	s_nop 1
	v_mov_b32_dpp v88, v124 row_ror:1 row_mask:0xf bank_mask:0xf
	v_mov_b32_dpp v85, v124 row_ror:15 row_mask:0xf bank_mask:0xf
	v_mov_b32_dpp v86, v125 row_ror:15 row_mask:0xf bank_mask:0xf
	v_mov_b32_dpp v87, v126 row_ror:15 row_mask:0xf bank_mask:0xf
	v_mov_b32_dpp v171, v108 row_ror:15 row_mask:0xf bank_mask:0xf
	v_mov_b32_dpp v172, v109 row_ror:15 row_mask:0xf bank_mask:0xf
	v_mov_b32_dpp v173, v110 row_ror:15 row_mask:0xf bank_mask:0xf
	v_mov_b32_dpp v89, v125 row_ror:1 row_mask:0xf bank_mask:0xf
	v_mov_b32_dpp v96, v126 row_ror:1 row_mask:0xf bank_mask:0xf
	v_mov_b32_dpp v97, v127 row_ror:1 row_mask:0xf bank_mask:0xf
	v_mov_b32_dpp v90, v127 row_ror:15 row_mask:0xf bank_mask:0xf
	v_mov_b32_dpp v134, v108 row_ror:1 row_mask:0xf bank_mask:0xf
	v_mov_b32_dpp v135, v109 row_ror:1 row_mask:0xf bank_mask:0xf
	v_mov_b32_dpp v137, v110 row_ror:1 row_mask:0xf bank_mask:0xf
	v_mov_b32_dpp v139, v111 row_ror:1 row_mask:0xf bank_mask:0xf
	v_mov_b32_dpp v174, v111 row_ror:15 row_mask:0xf bank_mask:0xf
	v_mov_b32_dpp v118, v100 row_ror:1 row_mask:0xf bank_mask:0xf
	v_mov_b32_dpp v136, v100 row_ror:15 row_mask:0xf bank_mask:0xf
	v_mov_b32_dpp v119, v101 row_ror:1 row_mask:0xf bank_mask:0xf
	v_mov_b32_dpp v138, v101 row_ror:15 row_mask:0xf bank_mask:0xf
	v_mov_b32_dpp v120, v98 row_ror:1 row_mask:0xf bank_mask:0xf
	v_mov_b32_dpp v149, v98 row_ror:15 row_mask:0xf bank_mask:0xf
	v_mov_b32_dpp v122, v99 row_ror:1 row_mask:0xf bank_mask:0xf
	v_mov_b32_dpp v170, v99 row_ror:15 row_mask:0xf bank_mask:0xf
	v_mov_b32_dpp v121, v93 row_ror:1 row_mask:0xf bank_mask:0xf
	v_mov_b32_dpp v92, v93 row_ror:15 row_mask:0xf bank_mask:0xf
	v_mov_b32_dpp v123, v77 row_ror:1 row_mask:0xf bank_mask:0xf
	v_mov_b32_dpp v76, v77 row_ror:15 row_mask:0xf bank_mask:0xf
	v_mov_b32_dpp v131, v81 row_ror:1 row_mask:0xf bank_mask:0xf
	v_mov_b32_dpp v80, v81 row_ror:15 row_mask:0xf bank_mask:0xf
	v_mov_b32_dpp v133, v79 row_ror:1 row_mask:0xf bank_mask:0xf
	v_mov_b32_dpp v78, v79 row_ror:15 row_mask:0xf bank_mask:0xf
	s_waitcnt lgkmcnt(14)
	v_cndmask_b32_e64 v95, v87, v173, s[6:7]
	v_cndmask_b32_e64 v91, v86, v172, s[6:7]
	v_cndmask_b32_e64 v87, v85, v171, s[6:7]
	s_waitcnt vmcnt(2)
	v_mov_b32_e32 v84, v64
	s_waitcnt vmcnt(0)
	v_mov_b32_e32 v85, v72
	v_mov_b32_e32 v86, v88
	v_pk_mul_f32 v[86:87], v[84:85], v[86:87]
	v_cndmask_b32_e64 v177, v90, v174, s[6:7]
	v_fma_f32 v86, v124, v68, v86
	v_add_f32_e32 v86, v86, v87
	v_mul_f32_e32 v86, v132, v86
	v_cndmask_b32_e64 v175, v86, v132, s[4:5]
	v_mov_b32_e32 v86, v65
	v_mov_b32_e32 v87, v73
	v_mov_b32_e32 v90, v89
	v_pk_mul_f32 v[90:91], v[86:87], v[90:91]
	v_mov_b32_e32 v94, v96
	v_fma_f32 v90, v125, v69, v90
	v_add_f32_e32 v90, v90, v91
	v_mul_f32_e32 v90, v128, v90
	v_cndmask_b32_e64 v178, v90, v128, s[4:5]
	v_mov_b32_e32 v90, v66
	v_mov_b32_e32 v91, v74
	v_pk_mul_f32 v[94:95], v[90:91], v[94:95]
	v_mov_b32_e32 v176, v97
	v_fma_f32 v94, v126, v70, v94
	v_add_f32_e32 v94, v94, v95
	v_mul_f32_e32 v94, v129, v94
	v_cndmask_b32_e64 v179, v94, v129, s[4:5]
	v_mov_b32_e32 v94, v67
	v_mov_b32_e32 v95, v75
	v_pk_mul_f32 v[176:177], v[94:95], v[176:177]
	s_nop 0
	v_fma_f32 v176, v127, v71, v176
	v_add_f32_e32 v176, v176, v177
	v_mul_f32_e32 v176, v130, v176
	v_cndmask_b32_e64 v177, v176, v130, s[4:5]
	v_cvt_pk_bf16_f32 v176, v175, v178
	v_cvt_pk_bf16_f32 v177, v179, v177
	v_lshl_add_u64 v[178:179], v[82:83], 1, s[48:49]
	global_store_dwordx2 v[178:179], v[176:177], off
	s_and_saveexec_b64 s[64:65], s[8:9]
	s_cbranch_execz .LBB0_304
	v_lshl_add_u64 v[178:179], v[82:83], 1, s[16:17]
	v_cvt_pk_bf16_f32 v176, v124, v125
	v_cvt_pk_bf16_f32 v177, v126, v127
	global_store_dwordx2 v[178:179], v[176:177], off

; __device__ __forceinline__ float silu_f(float x) { return x * __builtin_amdgcn_rcpf(1.f + __expf(-x)); }
;     __device__ __forceinline__ void operator()(const f32x4 (&acc)[2][2][4][2], const Unit& u, int wr, int wc, int fr, int fq) const {
;     ...
;             for (int m = 0; m < 4; ++m) rstd[ai][m] = (float)ss[r0 + ai * HALF + m * 16] * (1.f / 16777216.f);
;         const f32x4 w0 = *(const f32x4*)(cw + ch), w1 = *(const f32x4*)(cw + 2048 + ch), w2 = *(const f32x4*)(cw + 4096 + ch);
;         const bool fuse = u.pm != 96;
;         const int lr = (lane & 48) | ((fr + 15) & 15), ll = (lane & 48) | ((fr + 1) & 15);
; #pragma unroll
;         for (int ai = 0; ai < 2; ++ai) {
;             f32x4 g[4], cu[4];
; #pragma unroll
;             for (int m = 0; m < 4; ++m) {
;                 const float rs = __builtin_amdgcn_rsqf(rstd[ai][m] * (1.f / 2048.f) + 1e-6f);
;                 const f32x4 b = acc[ai][0][m][0] * rs, z = acc[ai][0][m][1] * rs, c = acc[ai][1][m][0] * rs, uu = acc[ai][1][m][1] * rs;
; #pragma unroll
;                 for (int j = 0; j < 4; ++j) { g[m][j] = b[j] * silu_f(z[j]); cu[m][j] = c[j] * uu[j]; }
;             }
.LBB0_311:
	s_or_b64 exec, exec, s[68:69]
	s_waitcnt vmcnt(6)
	v_ffbh_u32_e32 v76, v163
	v_min_u32_e32 v78, 32, v76
	v_lshlrev_b64 v[76:77], v78, v[162:163]
	v_min_u32_e32 v76, 1, v76
	v_or_b32_e32 v76, v77, v76
	v_cvt_f32_u32_e32 v76, v76
	v_sub_u32_e32 v77, 32, v78
	v_add_u32_e32 v82, 0x80, v148
	v_ashrrev_i32_e32 v83, 31, v82
	v_ldexp_f32 v76, v76, v77
	v_mul_f32_e32 v86, 0x33800000, v76
	s_waitcnt vmcnt(5)
	v_ffbh_u32_e32 v76, v159
	v_min_u32_e32 v78, 32, v76
	v_lshlrev_b64 v[76:77], v78, v[158:159]
	v_min_u32_e32 v76, 1, v76
	v_or_b32_e32 v76, v77, v76
	v_cvt_f32_u32_e32 v76, v76
	v_sub_u32_e32 v77, 32, v78
	v_add_u32_e32 v80, 0x90, v148
	v_ldexp_f32 v76, v76, v77
	v_mul_f32_e32 v87, 0x33800000, v76
	s_waitcnt vmcnt(4)
	v_ffbh_u32_e32 v76, v157
	v_min_u32_e32 v84, 32, v76
	v_lshlrev_b64 v[76:77], v84, v[156:157]
	v_min_u32_e32 v76, 1, v76
	v_or_b32_e32 v76, v77, v76
	v_cvt_f32_u32_e32 v76, v76
	v_sub_u32_e32 v77, 32, v84
	v_add_u32_e32 v78, 0xa0, v148
	v_ashrrev_i32_e32 v81, 31, v80
	v_ldexp_f32 v76, v76, v77
	s_waitcnt vmcnt(3)
	v_ffbh_u32_e32 v77, v153
	v_min_u32_e32 v89, 32, v77
	v_fmamk_f32 v77, v86, 0x3a000000, v227
	v_rsq_f32_e32 v86, v77
	v_lshlrev_b64 v[84:85], v89, v[152:153]
	v_min_u32_e32 v77, 1, v84
	v_or_b32_e32 v77, v85, v77
	v_mul_f32_e32 v60, v60, v86
	v_cvt_f32_u32_e32 v84, v77
	v_mul_f32_e32 v77, 0xbfb8aa3b, v60
	v_exp_f32_e32 v85, v77
	v_mul_f32_e32 v56, v56, v86
	v_mul_f32_e32 v52, v52, v86
	v_mul_f32_e32 v48, v48, v86
	v_add_f32_e32 v85, 1.0, v85
	v_rcp_f32_e32 v85, v85
	v_mul_f32_e32 v48, v52, v48
	v_mul_f32_e32 v52, v57, v86
	v_mul_f32_e32 v53, v53, v86
	v_mul_f32_e32 v60, v60, v85
	v_mul_f32_e32 v56, v56, v60
	v_mul_f32_e32 v60, v61, v86
	v_mul_f32_e32 v61, 0xbfb8aa3b, v60
	v_exp_f32_e32 v61, v61
	v_mul_f32_e32 v49, v49, v86
	v_mul_f32_e32 v49, v53, v49
	v_mul_f32_e32 v53, v58, v86
	v_add_f32_e32 v57, 1.0, v61
	v_mul_f32_e32 v61, v62, v86
	v_rcp_f32_e32 v57, v57
	v_mul_f32_e32 v62, 0xbfb8aa3b, v61
	v_exp_f32_e32 v62, v62
	v_mul_f32_e32 v54, v54, v86
	v_mul_f32_e32 v57, v60, v57
	v_mul_f32_e32 v52, v52, v57
	v_add_f32_e32 v57, 1.0, v62
	v_rcp_f32_e32 v57, v57
	v_mul_f32_e32 v50, v50, v86
	v_fmamk_f32 v58, v87, 0x3a000000, v227
	v_mul_f32_e32 v50, v54, v50
	v_mul_f32_e32 v57, v61, v57
	v_mul_f32_e32 v54, v63, v86
	v_rsq_f32_e32 v58, v58
	v_mul_f32_e32 v53, v53, v57
	v_mul_f32_e32 v57, 0xbfb8aa3b, v54
	v_exp_f32_e32 v57, v57
	v_mul_f32_e32 v60, v44, v58
	v_mul_f32_e32 v44, 0xbfb8aa3b, v60
	v_exp_f32_e32 v44, v44
	v_add_f32_e32 v57, 1.0, v57
	v_rcp_f32_e32 v57, v57
	v_mul_f32_e32 v40, v40, v58
	v_add_f32_e32 v44, 1.0, v44
	v_mul_f32_e32 v45, v45, v58
	v_mul_f32_e32 v54, v54, v57
	v_rcp_f32_e32 v57, v44
	v_mul_f32_e32 v44, v51, v86
	v_mul_f32_e32 v36, v36, v58
	v_mul_f32_e32 v32, v32, v58
	v_mul_f32_e32 v51, v60, v57
	v_mul_f32_e32 v40, v40, v51
	v_mul_f32_e32 v51, 0xbfb8aa3b, v45
	v_exp_f32_e32 v51, v51
	v_mul_f32_e32 v32, v36, v32
	v_mul_f32_e32 v36, v41, v58
	v_mul_f32_e32 v46, v46, v58
	v_add_f32_e32 v41, 1.0, v51
	v_rcp_f32_e32 v41, v41
	v_mul_f32_e32 v51, 0xbfb8aa3b, v46
	v_exp_f32_e32 v51, v51
	v_mul_f32_e32 v88, 0x33800000, v76
	v_mul_f32_e32 v41, v45, v41
	v_mul_f32_e32 v36, v36, v41
	v_add_f32_e32 v41, 1.0, v51
	v_rcp_f32_e32 v41, v41
	v_mul_f32_e32 v37, v37, v58
	v_mul_f32_e32 v33, v33, v58
	v_mul_f32_e32 v38, v38, v58
	v_mul_f32_e32 v34, v34, v58
	v_mul_f32_e32 v33, v37, v33
	v_mul_f32_e32 v37, v42, v58
	v_mul_f32_e32 v41, v46, v41
	v_mul_f32_e32 v34, v38, v34
	v_mul_f32_e32 v38, v47, v58
	v_fmamk_f32 v42, v88, 0x3a000000, v227
	v_mul_f32_e32 v37, v37, v41
	v_mul_f32_e32 v41, 0xbfb8aa3b, v38
	v_rsq_f32_e32 v42, v42
	v_exp_f32_e32 v41, v41
	v_mul_f32_e32 v39, v39, v58
	v_mul_f32_e32 v35, v35, v58
	v_mul_f32_e32 v28, v28, v42
	v_add_f32_e32 v41, 1.0, v41
	v_mul_f32_e32 v45, 0xbfb8aa3b, v28
	v_rcp_f32_e32 v41, v41
	v_exp_f32_e32 v45, v45
	v_mul_f32_e32 v24, v24, v42
	v_mul_f32_e32 v29, v29, v42
	v_mul_f32_e32 v38, v38, v41
	v_add_f32_e32 v41, 1.0, v45
	v_rcp_f32_e32 v41, v41
	v_mul_f32_e32 v35, v39, v35
	v_mul_f32_e32 v20, v20, v42
	v_mul_f32_e32 v16, v16, v42
	v_mul_f32_e32 v28, v28, v41
	v_mul_f32_e32 v24, v24, v28
	v_mul_f32_e32 v28, 0xbfb8aa3b, v29
	v_exp_f32_e32 v39, v28
	v_mul_f32_e32 v28, v20, v16
	v_mul_f32_e32 v30, v30, v42
	v_mul_f32_e32 v16, v25, v42
	v_add_f32_e32 v20, 1.0, v39
	v_rcp_f32_e32 v20, v20
	v_mul_f32_e32 v25, 0xbfb8aa3b, v30
	v_exp_f32_e32 v25, v25
	v_mul_f32_e32 v17, v17, v42
	v_mul_f32_e32 v20, v29, v20
	v_mul_f32_e32 v29, v16, v20
	v_add_f32_e32 v20, 1.0, v25
	v_rcp_f32_e32 v20, v20
	v_mul_f32_e32 v16, v21, v42
	v_mul_f32_e32 v25, v16, v17
	v_mul_f32_e32 v16, v26, v42
	v_mul_f32_e32 v17, v30, v20
	v_mul_f32_e32 v26, v16, v17
	v_mul_f32_e32 v16, v31, v42
	v_mul_f32_e32 v17, 0xbfb8aa3b, v16
	v_sub_u32_e32 v89, 32, v89
	v_exp_f32_e32 v17, v17
	v_ldexp_f32 v84, v84, v89
	v_mul_f32_e32 v84, 0x33800000, v84
	v_mul_f32_e32 v20, v22, v42
	v_mul_f32_e32 v18, v18, v42
	v_mul_f32_e32 v22, v20, v18
	v_fmamk_f32 v20, v84, 0x3a000000, v227
	v_add_f32_e32 v17, 1.0, v17
	v_rsq_f32_e32 v20, v20
	v_rcp_f32_e32 v17, v17
	v_mul_f32_e32 v18, v27, v42
	v_add_u32_e32 v76, 0xb0, v148
	v_mul_f32_e32 v12, v12, v20
	v_mul_f32_e32 v16, v16, v17
	v_mul_f32_e32 v17, 0xbfb8aa3b, v12
	v_exp_f32_e32 v17, v17
	v_mul_f32_e32 v27, v18, v16
	v_mul_f32_e32 v16, v23, v42
	v_mul_f32_e32 v18, v19, v42
	v_mul_f32_e32 v23, v16, v18
	v_add_f32_e32 v16, 1.0, v17
	v_mul_f32_e32 v17, v13, v20
	v_rcp_f32_e32 v16, v16
	v_mul_f32_e32 v13, 0xbfb8aa3b, v17
	v_exp_f32_e32 v13, v13
	v_mul_f32_e32 v8, v8, v20
	v_mul_f32_e32 v12, v12, v16
	v_mul_f32_e32 v30, v8, v12
	v_add_f32_e32 v8, 1.0, v13
	v_rcp_f32_e32 v8, v8
	v_mul_f32_e32 v4, v4, v20
	v_mul_f32_e32 v0, v0, v20
	v_mul_f32_e32 v13, v4, v0
	v_mul_f32_e32 v0, v9, v20
	v_mul_f32_e32 v4, v17, v8
	v_mul_f32_e32 v31, v0, v4
	v_mul_f32_e32 v4, v14, v20
	v_mul_f32_e32 v0, v5, v20
	v_mul_f32_e32 v5, 0xbfb8aa3b, v4
	v_exp_f32_e32 v5, v5
	v_mul_f32_e32 v8, v15, v20
	v_mul_f32_e32 v9, 0xbfb8aa3b, v8
	v_exp_f32_e32 v9, v9
	v_add_f32_e32 v5, 1.0, v5
	v_rcp_f32_e32 v5, v5
	v_mul_f32_e32 v1, v1, v20
	v_mul_f32_e32 v1, v0, v1
	v_mul_f32_e32 v0, v10, v20
	v_mul_f32_e32 v4, v4, v5
	v_mul_f32_e32 v39, v0, v4
	v_add_f32_e32 v4, 1.0, v9
	v_rcp_f32_e32 v4, v4
	v_mul_f32_e32 v0, v6, v20
	v_mul_f32_e32 v2, v2, v20
	v_mul_f32_e32 v5, v0, v2
	v_mul_f32_e32 v0, v11, v20
	v_mul_f32_e32 v2, v8, v4
	v_mul_f32_e32 v59, v59, v86
	v_mul_f32_e32 v55, v55, v86
	v_mul_f32_e32 v43, v43, v58
	v_mul_f32_e32 v41, v0, v2
	v_mul_f32_e32 v0, v7, v20
	v_mul_f32_e32 v2, v3, v20
	v_lshlrev_b64 v[6:7], 11, v[82:83]
	v_ashrrev_i32_e32 v79, 31, v78
	v_ashrrev_i32_e32 v77, 31, v76
	v_mul_f32_e32 v54, v59, v54
	v_mul_f32_e32 v44, v55, v44
	v_mul_f32_e32 v38, v43, v38
	v_mul_f32_e32 v3, v0, v2
	s_andn2_b64 vcc, exec, s[72:73]
	v_lshl_add_u64 v[6:7], v[6:7], 0, v[146:147]
	s_cbranch_vccnz .LBB0_317
; __device__ __forceinline__ unsigned cvt_pk_bf16(float lo, float hi) { unsigned r; asm volatile("v_cvt_pk_bf16_f32 %0, %1, %2" : "=v"(r) : "v"(lo), "v"(hi)); return r; }
;     __device__ __forceinline__ void operator()(const f32x4 (&acc)[2][2][4][2], const Unit& u, int wr, int wc, int fr, int fq) const {
;     ...
;             if (fuse) {
;                 f32x4 R[4], L[4];
; #pragma unroll
;                 for (int m = 0; m < 4; ++m)
; #pragma unroll
;                     for (int j = 0; j < 4; ++j) { R[m][j] = __shfl(cu[m][j], lr); L[m][j] = __shfl(cu[m][j], ll); }
; #pragma unroll
;                 for (int m = 0; m < 4; ++m) {
;                     const int r = r0 + ai * HALF + m * 16;
;                     const f32x4 prev = (fr == 0) ? R[m > 0 ? m - 1 : 0] : R[m], next = (fr == 15) ? L[m < 3 ? m + 1 : 3] : L[m];
;                     const bool edge = (m == 0 && fr == 0) || (m == 3 && fr == 15);
;                     f32x4 y;
; #pragma unroll
;                     for (int j = 0; j < 4; ++j) { const float t = g[m][j] * (prev[j] * w0[j] + cu[m][j] * w1[j] + next[j] * w2[j]); y[j] = edge ? g[m][j] : t; }
;                     const size_t off = (size_t)r * 2048 + ch;
;                     u32x2 o1; o1.x = cvt_pk_bf16(y[0], y[1]); o1.y = cvt_pk_bf16(y[2], y[3]);
;                     *(u32x2*)(G + off) = o1;
;                     if ((m == 0 && fr <= 1) || (m == 3 && fr >= 14)) { u32x2 o2; o2.x = cvt_pk_bf16(cu[m][0], cu[m][1]); o2.y = cvt_pk_bf16(cu[m][2], cu[m][3]); *(u32x2*)(CU + off) = o2; }
	v_and_b32_e32 v0, 64, v232
	v_or_b32_e32 v2, v0, v167
	v_or_b32_e32 v0, v0, v168
	v_lshlrev_b32_e32 v2, 2, v2
	v_lshlrev_b32_e32 v8, 2, v0
	s_nop 1
	v_mov_b32_dpp v14, v48 row_ror:1 row_mask:0xf bank_mask:0xf
	v_mov_b32_dpp v9, v48 row_ror:15 row_mask:0xf bank_mask:0xf
	v_mov_b32_dpp v10, v49 row_ror:15 row_mask:0xf bank_mask:0xf
	v_mov_b32_dpp v11, v50 row_ror:15 row_mask:0xf bank_mask:0xf
	v_mov_b32_dpp v84, v32 row_ror:15 row_mask:0xf bank_mask:0xf
	v_mov_b32_dpp v85, v33 row_ror:15 row_mask:0xf bank_mask:0xf
	v_mov_b32_dpp v86, v34 row_ror:15 row_mask:0xf bank_mask:0xf
	v_mov_b32_dpp v15, v49 row_ror:1 row_mask:0xf bank_mask:0xf
	v_mov_b32_dpp v20, v50 row_ror:1 row_mask:0xf bank_mask:0xf
	v_mov_b32_dpp v21, v44 row_ror:1 row_mask:0xf bank_mask:0xf
	v_mov_b32_dpp v16, v44 row_ror:15 row_mask:0xf bank_mask:0xf
	v_mov_b32_dpp v58, v32 row_ror:1 row_mask:0xf bank_mask:0xf
	v_mov_b32_dpp v59, v33 row_ror:1 row_mask:0xf bank_mask:0xf
	v_mov_b32_dpp v61, v34 row_ror:1 row_mask:0xf bank_mask:0xf
	v_mov_b32_dpp v63, v35 row_ror:1 row_mask:0xf bank_mask:0xf
	v_mov_b32_dpp v87, v35 row_ror:15 row_mask:0xf bank_mask:0xf
	v_mov_b32_dpp v42, v28 row_ror:1 row_mask:0xf bank_mask:0xf
	v_mov_b32_dpp v60, v28 row_ror:15 row_mask:0xf bank_mask:0xf
	v_mov_b32_dpp v43, v25 row_ror:1 row_mask:0xf bank_mask:0xf
	v_mov_b32_dpp v62, v25 row_ror:15 row_mask:0xf bank_mask:0xf
	v_mov_b32_dpp v45, v22 row_ror:1 row_mask:0xf bank_mask:0xf
	v_mov_b32_dpp v82, v22 row_ror:15 row_mask:0xf bank_mask:0xf
	v_mov_b32_dpp v47, v23 row_ror:1 row_mask:0xf bank_mask:0xf
	v_mov_b32_dpp v83, v23 row_ror:15 row_mask:0xf bank_mask:0xf
	v_mov_b32_dpp v46, v13 row_ror:1 row_mask:0xf bank_mask:0xf
	v_mov_b32_dpp v12, v13 row_ror:15 row_mask:0xf bank_mask:0xf
	v_mov_b32_dpp v51, v1 row_ror:1 row_mask:0xf bank_mask:0xf
	v_mov_b32_dpp v0, v1 row_ror:15 row_mask:0xf bank_mask:0xf
	v_mov_b32_dpp v55, v5 row_ror:1 row_mask:0xf bank_mask:0xf
	v_mov_b32_dpp v4, v5 row_ror:15 row_mask:0xf bank_mask:0xf
	v_mov_b32_dpp v57, v3 row_ror:1 row_mask:0xf bank_mask:0xf
	v_mov_b32_dpp v2, v3 row_ror:15 row_mask:0xf bank_mask:0xf
	s_waitcnt lgkmcnt(14)
	v_cndmask_b32_e64 v19, v11, v86, s[6:7]
	v_cndmask_b32_e64 v17, v10, v85, s[6:7]
	v_cndmask_b32_e64 v11, v9, v84, s[6:7]
	s_waitcnt vmcnt(2)
	v_mov_b32_e32 v8, v64
	s_waitcnt vmcnt(0)
	v_mov_b32_e32 v9, v72
	v_mov_b32_e32 v10, v14
	v_pk_mul_f32 v[10:11], v[8:9], v[10:11]
	v_cndmask_b32_e64 v89, v16, v87, s[6:7]
	v_fma_f32 v10, v68, v48, v10
	v_add_f32_e32 v10, v10, v11
	v_mul_f32_e32 v10, v56, v10
	v_cndmask_b32_e64 v90, v10, v56, s[4:5]
	v_mov_b32_e32 v10, v65
	v_mov_b32_e32 v11, v73
	v_mov_b32_e32 v16, v15
	v_pk_mul_f32 v[16:17], v[10:11], v[16:17]
	v_mov_b32_e32 v18, v20
	v_fma_f32 v16, v69, v49, v16
	v_add_f32_e32 v16, v16, v17
	v_mul_f32_e32 v16, v52, v16
	v_cndmask_b32_e64 v91, v16, v52, s[4:5]
	v_mov_b32_e32 v16, v66
	v_mov_b32_e32 v17, v74
	v_pk_mul_f32 v[18:19], v[16:17], v[18:19]
	v_mov_b32_e32 v88, v21
	v_fma_f32 v18, v70, v50, v18
	v_add_f32_e32 v18, v18, v19
	v_mul_f32_e32 v18, v53, v18
	v_cndmask_b32_e64 v92, v18, v53, s[4:5]
	v_mov_b32_e32 v18, v67
	v_mov_b32_e32 v19, v75
	v_pk_mul_f32 v[88:89], v[18:19], v[88:89]
	s_nop 0
	v_fma_f32 v88, v71, v44, v88
	v_add_f32_e32 v88, v88, v89
	v_mul_f32_e32 v88, v54, v88
	v_cndmask_b32_e64 v89, v88, v54, s[4:5]
	v_cvt_pk_bf16_f32 v88, v90, v91
	v_lshl_add_u64 v[90:91], v[6:7], 1, s[48:49]
	v_cvt_pk_bf16_f32 v89, v92, v89
	global_store_dwordx2 v[90:91], v[88:89], off
	s_and_saveexec_b64 s[64:65], s[8:9]
	s_cbranch_execz .LBB0_314
	v_lshl_add_u64 v[90:91], v[6:7], 1, s[16:17]
	v_cvt_pk_bf16_f32 v88, v48, v49
	v_cvt_pk_bf16_f32 v89, v50, v44
	global_store_dwordx2 v[90:91], v[88:89], off
